# gate scans in M1 and M3 by DPP row shifts and row broadcasts instead of ds_bpermute chains
# speedup vs baseline: 1.0056x; 1.0030x over previous
.LBB0_68:
	s_mov_b64 s[8:9], s[36:37]
	v_mov_b32_e32 v187, v224
	s_ashr_i32 s0, s5, 7
	s_and_b32 s1, s5, 0x7f
	s_load_dwordx2 s[2:3], s[8:9], 0xa8
	s_lshl_b32 s14, s0, 13
	s_lshl_b32 s10, s1, 6
	s_waitcnt vmcnt(0)
	v_and_b32_e32 v2, 63, v187
	s_or_b32 s15, s10, s14
	v_or_b32_e32 v0, s15, v2
	v_ashrrev_i32_e32 v178, 7, v187
	v_ashrrev_i32_e32 v1, 31, v0
	v_ashrrev_i32_e32 v179, 31, v178
	s_waitcnt lgkmcnt(0)
	v_lshl_add_u64 v[0:1], v[0:1], 4, s[2:3]
	v_lshl_add_u64 v[0:1], v[178:179], 2, v[0:1]
	s_mov_b32 s10, 0x80000
	v_add_co_u32_e32 v4, vcc, s10, v0
	v_and_b32_e32 v162, 0xffffff80, v187
	s_nop 0
	v_addc_co_u32_e32 v5, vcc, 0, v1, vcc
	global_load_dword v3, v[4:5], off
	global_load_dword v6, v[0:1], off
	v_cmp_lt_i32_e32 vcc, v227, v237
	v_cmp_eq_u32_e64 s[38:39], 0, v2
	v_cmp_gt_u32_e64 s[40:41], 2, v2
	v_cndmask_b32_e32 v0, v227, v236, vcc
	v_lshlrev_b32_e32 v7, 2, v0
	v_cmp_lt_i32_e32 vcc, v228, v237
	v_lshl_add_u32 v0, s0, 9, v162
	v_or_b32_e32 v0, s1, v0
	v_cndmask_b32_e32 v1, v228, v236, vcc
	v_cmp_lt_i32_e32 vcc, v229, v237
	v_lshlrev_b32_e32 v8, 2, v1
	v_ashrrev_i32_e32 v1, 31, v0
	v_cndmask_b32_e32 v4, v229, v236, vcc
	v_lshlrev_b32_e32 v9, 2, v4
	v_lshl_add_u64 v[4:5], v[0:1], 2, s[2:3]
	s_mov_b32 s0, 0x104000
	v_add_co_u32_e32 v4, vcc, s0, v4
	v_cmp_gt_u32_e64 s[42:43], 4, v2
	s_nop 0
	v_addc_co_u32_e32 v5, vcc, 0, v5, vcc
	global_load_dword v36, v[4:5], off
	v_lshlrev_b64 v[214:215], 9, v[0:1]
	v_lshl_add_u64 v[214:215], s[2:3], 0, v[214:215]
	v_lshlrev_b32_e32 v216, 2, v2
	v_mov_b32_e32 v217, v113
	v_lshl_add_u64 v[214:215], v[214:215], 0, v[216:217]
	v_add_co_u32_e32 v214, vcc, 0x300000, v214
	s_nop 0
	v_addc_co_u32_e32 v215, vcc, 0, v215, vcc
	global_load_dword v218, v[214:215], off
	global_load_dword v219, v[214:215], off offset:256
	v_cmp_lt_i32_e32 vcc, v230, v237
	v_cmp_gt_u32_e64 s[44:45], 8, v2
	v_cmp_gt_u32_e64 s[46:47], 16, v2
	v_cndmask_b32_e32 v5, v230, v236, vcc
	v_cmp_lt_i32_e32 vcc, v231, v237
	v_lshl_add_u32 v37, v162, 2, s13
	s_waitcnt vmcnt(4)
	v_mov_b32_e32 v4, v3
	s_nop 1
	v_add_f32_dpp v4, v4, v4 row_shr:1 row_mask:0xf bank_mask:0xf
	s_nop 1
	v_add_f32_dpp v4, v4, v4 row_shr:2 row_mask:0xf bank_mask:0xf
	s_nop 1
	v_add_f32_dpp v4, v4, v4 row_shr:4 row_mask:0xf bank_mask:0xf
	s_nop 1
	v_add_f32_dpp v4, v4, v4 row_shr:8 row_mask:0xf bank_mask:0xf
	s_nop 1
	v_add_f32_dpp v4, v4, v4 row_bcast:15 row_mask:0xa bank_mask:0xf
	s_nop 1
	v_add_f32_dpp v4, v4, v4 row_bcast:31 row_mask:0xc bank_mask:0xf
	s_waitcnt vmcnt(3)
	v_sub_f32_e32 v5, v6, v4
	v_mov_b32_e32 v6, v5
	s_nop 1
	v_max_f32_dpp v6, v6, v6 row_shr:1 row_mask:0xf bank_mask:0xf
	s_nop 1
	v_max_f32_dpp v6, v6, v6 row_shr:2 row_mask:0xf bank_mask:0xf
	s_nop 1
	v_max_f32_dpp v6, v6, v6 row_shr:4 row_mask:0xf bank_mask:0xf
	s_nop 1
	v_max_f32_dpp v6, v6, v6 row_shr:8 row_mask:0xf bank_mask:0xf
	s_nop 1
	v_max_f32_dpp v6, v6, v6 row_bcast:15 row_mask:0xa bank_mask:0xf
	s_nop 1
	v_max_f32_dpp v6, v6, v6 row_bcast:31 row_mask:0xc bank_mask:0xf
	v_lshlrev_b32_e32 v8, 8, v178
	v_add_u32_e32 v39, s7, v8
	v_add_u32_e32 v38, s12, v8
	v_bfe_u32 v3, v187, 6, 1
	v_cmp_eq_u32_e64 s[38:39], 0, v3
	s_and_saveexec_b64 s[0:1], s[38:39]
	s_cbranch_execz .LBB0_70
	v_lshlrev_b32_e32 v8, 6, v178
	v_lshlrev_b32_e32 v8, 2, v8
	s_waitcnt vmcnt(0)
	v_max_f32_e32 v7, v36, v36
	v_lshlrev_b32_e32 v112, 2, v2
	v_max_f32_e32 v6, v7, v6
	v_add3_u32 v7, s6, v8, v112
	ds_write_b32 v7, v5
	v_add_u32_e32 v5, v39, v112
	v_add_f32_e32 v6, v4, v6
	ds_write_b32 v5, v4
	v_add_u32_e32 v4, v38, v112
	ds_write_b32 v4, v6
	v_lshlrev_b64 v[4:5], 9, v[0:1]
	v_lshl_add_u64 v[4:5], s[2:3], 0, v[4:5]
	v_lshl_add_u64 v[4:5], v[4:5], 0, v[112:113]
	s_mov_b64 s[10:11], 0x300000
	v_lshl_add_u64 v[6:7], v[4:5], 0, s[10:11]
	v_add_co_u32_e32 v4, vcc, 0x300000, v4
	s_nop 0
	v_addc_co_u32_e32 v5, vcc, 0, v5, vcc
	v_add_u32_e32 v5, v37, v112
	s_waitcnt vmcnt(0)
	ds_write2st64_b32 v5, v218, v219 offset1:1

.LBB0_311:
	s_mov_b64 s[0:1], s[36:37]
	s_waitcnt vmcnt(9)
	v_mov_b32_e32 v104, v224
	s_load_dwordx2 s[2:3], s[0:1], 0xa8
	s_ashr_i32 s4, s12, 7
	s_waitcnt vmcnt(1)
	v_bfe_u32 v99, v104, 6, 1
	v_and_b32_e32 v0, 0xffffff80, v104
	s_and_b32 s5, s12, 0x7f
	v_lshl_add_u32 v1, s4, 9, v0
	v_cmp_eq_u32_e32 vcc, 0, v99
	v_or_b32_e32 v96, s5, v1
	v_and_b32_e32 v1, 64, v104
	v_cndmask_b32_e32 v112, v234, v235, vcc
	v_and_b32_e32 v69, 15, v104
	v_cmp_ne_u32_e64 s[38:39], 0, v1
	s_waitcnt lgkmcnt(0)
	v_lshl_add_u64 v[2:3], s[2:3], 0, v[112:113]
	v_ashrrev_i32_e32 v1, 31, v0
	s_lshl_b32 s0, s4, 13
	s_lshl_b32 s1, s5, 6
	v_lshl_add_u64 v[0:1], v[0:1], 1, v[2:3]
	v_lshlrev_b32_e32 v112, 4, v69
	v_bfe_u32 v68, v104, 4, 2
	s_or_b32 s0, s1, s0
	v_lshl_add_u64 v[0:1], v[0:1], 0, v[112:113]
	s_mov_b64 s[4:5], 0x6000000
	v_lshl_add_u64 v[0:1], v[0:1], 0, s[4:5]
	v_or_b32_e32 v2, s0, v68
	s_movk_i32 s1, 0x1c00
	v_mad_i64_i32 v[2:3], s[4:5], v2, s1, v[0:1]
	v_or_b32_e32 v85, 4, v68
	global_load_dwordx4 v[60:63], v[2:3], off
	v_or_b32_e32 v2, s0, v85
	v_mad_i64_i32 v[2:3], s[4:5], v2, s1, v[0:1]
	v_or_b32_e32 v84, 8, v68
	global_load_dwordx4 v[56:59], v[2:3], off
	v_or_b32_e32 v2, s0, v84
	v_mad_i64_i32 v[2:3], s[4:5], v2, s1, v[0:1]
	v_or_b32_e32 v83, 12, v68
	global_load_dwordx4 v[52:55], v[2:3], off
	v_or_b32_e32 v2, s0, v83
	v_mad_i64_i32 v[2:3], s[4:5], v2, s1, v[0:1]
	v_or_b32_e32 v82, 16, v68
	global_load_dwordx4 v[48:51], v[2:3], off
	v_or_b32_e32 v2, s0, v82
	v_mad_i64_i32 v[2:3], s[4:5], v2, s1, v[0:1]
	v_or_b32_e32 v80, 20, v68
	global_load_dwordx4 v[44:47], v[2:3], off
	v_or_b32_e32 v2, s0, v80
	v_mad_i64_i32 v[2:3], s[4:5], v2, s1, v[0:1]
	v_or_b32_e32 v79, 24, v68
	global_load_dwordx4 v[40:43], v[2:3], off
	v_or_b32_e32 v2, s0, v79
	v_mad_i64_i32 v[2:3], s[4:5], v2, s1, v[0:1]
	v_or_b32_e32 v78, 28, v68
	global_load_dwordx4 v[36:39], v[2:3], off
	v_or_b32_e32 v2, s0, v78
	v_mad_i64_i32 v[2:3], s[4:5], v2, s1, v[0:1]
	v_or_b32_e32 v77, 32, v68
	global_load_dwordx4 v[32:35], v[2:3], off
	v_or_b32_e32 v2, s0, v77
	v_mad_i64_i32 v[2:3], s[4:5], v2, s1, v[0:1]
	v_or_b32_e32 v76, 36, v68
	global_load_dwordx4 v[28:31], v[2:3], off
	v_or_b32_e32 v2, s0, v76
	v_mad_i64_i32 v[2:3], s[4:5], v2, s1, v[0:1]
	v_or_b32_e32 v75, 40, v68
	global_load_dwordx4 v[24:27], v[2:3], off
	v_or_b32_e32 v2, s0, v75
	v_mad_i64_i32 v[2:3], s[4:5], v2, s1, v[0:1]
	v_or_b32_e32 v74, 44, v68
	global_load_dwordx4 v[20:23], v[2:3], off
	v_or_b32_e32 v2, s0, v74
	v_mad_i64_i32 v[2:3], s[4:5], v2, s1, v[0:1]
	v_or_b32_e32 v73, 48, v68
	global_load_dwordx4 v[16:19], v[2:3], off
	v_or_b32_e32 v2, s0, v73
	v_mad_i64_i32 v[2:3], s[4:5], v2, s1, v[0:1]
	v_or_b32_e32 v72, 52, v68
	v_and_b32_e32 v67, 63, v104
	global_load_dwordx4 v[12:15], v[2:3], off
	v_or_b32_e32 v2, s0, v72
	v_mad_i64_i32 v[2:3], s[4:5], v2, s1, v[0:1]
	v_or_b32_e32 v71, 56, v68
	v_or_b32_e32 v86, s0, v67
	v_ashrrev_i32_e32 v64, 7, v104
	global_load_dwordx4 v[8:11], v[2:3], off
	v_or_b32_e32 v2, s0, v71
	v_ashrrev_i32_e32 v87, 31, v86
	v_mad_i64_i32 v[2:3], s[4:5], v2, s1, v[0:1]
	v_or_b32_e32 v70, 60, v68
	v_ashrrev_i32_e32 v65, 31, v64
	v_lshl_add_u64 v[86:87], v[86:87], 4, s[2:3]
	global_load_dwordx4 v[4:7], v[2:3], off
	v_or_b32_e32 v2, s0, v70
	v_lshl_add_u64 v[86:87], v[64:65], 2, v[86:87]
	s_mov_b32 s0, 0x80000
	v_add_co_u32_e32 v88, vcc, s0, v86
	v_mad_i64_i32 v[0:1], s[4:5], v2, s1, v[0:1]
	s_nop 0
	v_addc_co_u32_e32 v89, vcc, 0, v87, vcc
	global_load_dwordx4 v[0:3], v[0:1], off
	s_nop 0
	global_load_dword v65, v[88:89], off
	global_load_dword v66, v[86:87], off
	v_cmp_lt_i32_e32 vcc, v227, v237
	v_xor_b32_e32 v86, 1, v236
	v_xor_b32_e32 v87, 2, v236
	v_cndmask_b32_e32 v81, v227, v236, vcc
	v_lshlrev_b32_e32 v81, 2, v81
	v_cmp_eq_u32_e32 vcc, 0, v67
	v_ashrrev_i32_e32 v97, 31, v96
	s_waitcnt vmcnt(1)
	v_mov_b32_e32 v81, v65
	s_nop 1
	v_add_f32_dpp v81, v81, v81 row_shr:1 row_mask:0xf bank_mask:0xf
	s_nop 1
	v_add_f32_dpp v81, v81, v81 row_shr:2 row_mask:0xf bank_mask:0xf
	s_nop 1
	v_add_f32_dpp v81, v81, v81 row_shr:4 row_mask:0xf bank_mask:0xf
	s_nop 1
	v_add_f32_dpp v81, v81, v81 row_shr:8 row_mask:0xf bank_mask:0xf
	s_nop 1
	v_add_f32_dpp v81, v81, v81 row_bcast:15 row_mask:0xa bank_mask:0xf
	s_nop 1
	v_add_f32_dpp v81, v81, v81 row_bcast:31 row_mask:0xc bank_mask:0xf
	s_waitcnt vmcnt(0)
	v_sub_f32_e32 v65, v66, v81
	v_mov_b32_e32 v86, v65
	s_nop 1
	v_max_f32_dpp v86, v86, v86 row_shr:1 row_mask:0xf bank_mask:0xf
	s_nop 1
	v_max_f32_dpp v86, v86, v86 row_shr:2 row_mask:0xf bank_mask:0xf
	s_nop 1
	v_max_f32_dpp v86, v86, v86 row_shr:4 row_mask:0xf bank_mask:0xf
	s_nop 1
	v_max_f32_dpp v86, v86, v86 row_shr:8 row_mask:0xf bank_mask:0xf
	s_nop 1
	v_max_f32_dpp v86, v86, v86 row_bcast:15 row_mask:0xa bank_mask:0xf
	s_nop 1
	v_max_f32_dpp v86, v86, v86 row_bcast:31 row_mask:0xc bank_mask:0xf
	s_nop 1
	v_readlane_b32 s6, v86, 63
	v_readlane_b32 s7, v81, 63
	s_nop 0
	v_mov_b32_e32 v66, s6
	v_mov_b32_e32 v81, s7
	v_or_b32_e32 v86, v99, v67
	v_cmp_eq_u32_e32 vcc, 0, v86
	s_and_saveexec_b64 s[0:1], vcc
	s_cbranch_execz .LBB0_313
	v_lshl_add_u64 v[86:87], v[96:97], 2, s[2:3]
	v_add_co_u32_e32 v88, vcc, 0x100000, v86
	s_nop 1
	v_addc_co_u32_e32 v89, vcc, 0, v87, vcc
	v_add_co_u32_e32 v86, vcc, 0x102000, v86
	s_waitcnt lgkmcnt(0)
	global_store_dword v[88:89], v81, off
	v_addc_co_u32_e32 v87, vcc, 0, v87, vcc
	global_store_dword v[86:87], v66, off
